# attention work queue: each workgroup's first item is static (its index within the XCD), only later items use the atomic counter
# speedup vs baseline: 1.0832x; 1.0115x over previous
; __global__ void __launch_bounds__(256, 2) hymba_mega(Params p) {
;     ...
;       const float lam_init = 0.8f - 0.6f * expf(-0.3f * (float)layer);
;       float d1 = 0.f, d2 = 0.f;
;       for (int i = 0; i < 32; ++i) {
;         d1 += p.lq1[layer * 32 + i] * p.lk1[layer * 32 + i];
;         d2 += p.lq2[layer * 32 + i] * p.lk2[layer * 32 + i];
;       }
;       const float lam = expf(d1) - expf(d2) + lam_init;
;       for (int rep = 0; rep < REP_ATT; ++rep) {
;       if (rep) xcd_barrier(gb);
;       unsigned* qctr = p.ctr + (rep * 2 + layer) * 8 + xcd;
.LBB0_193:
	v_readlane_b32 s2, v251, 17
	v_readlane_b32 s3, v251, 18
	s_or_b64 exec, exec, s[0:1]
	v_readlane_b32 s64, v250, 26
	s_mov_b64 s[42:43], s[26:27]
	s_mov_b32 s36, s23
	s_waitcnt lgkmcnt(0)
	v_cvt_f32_u32_e32 v0, s64
	s_mov_b32 s37, 0x3fb8aa3b
	s_mov_b32 s39, s25
	s_lshl_b32 s38, s64, 5
	v_mul_f32_e32 v0, 0xbe99999a, v0
	v_mul_f32_e32 v2, 0x3fb8aa3b, v0
	v_readlane_b32 s12, v251, 0
	s_xor_b64 s[70:71], s[34:35], -1
	v_fma_f32 v3, v0, s37, -v2
	v_rndne_f32_e32 v4, v2
	s_lshl_b64 s[4:5], s[38:39], 2
	v_readlane_b32 s18, v251, 6
	v_fmac_f32_e32 v3, 0x32a5705f, v0
	v_sub_f32_e32 v2, v2, v4
	v_readlane_b32 s19, v251, 7
	s_add_u32 s6, s18, s4
	v_add_f32_e32 v2, v2, v3
	v_readlane_b32 s20, v251, 8
	s_addc_u32 s7, s19, s5
	v_exp_f32_e32 v2, v2
	v_cvt_i32_f32_e32 v3, v4
	v_readlane_b32 s21, v251, 9
	s_add_u32 s2, s20, s4
	v_readlane_b32 s22, v251, 10
	s_addc_u32 s3, s21, s5
	v_readlane_b32 s23, v251, 11
	s_add_u32 s0, s22, s4
	s_mov_b32 s40, 0xc2ce8ed0
	v_readlane_b32 s24, v251, 12
	s_addc_u32 s1, s23, s5
	v_ldexp_f32 v2, v2, v3
	v_cmp_ngt_f32_e32 vcc, s40, v0
	s_mov_b32 s46, 0x42b17218
	v_readlane_b32 s25, v251, 13
	s_add_u32 s4, s24, s4
	v_cndmask_b32_e32 v2, 0, v2, vcc
	v_cmp_nlt_f32_e32 vcc, s46, v0
	s_addc_u32 s5, s25, s5
	s_barrier
	v_cndmask_b32_e32 v0, v195, v2, vcc
	global_load_dwordx4 v[2:5], v1, s[6:7] offset:48
	global_load_dwordx4 v[6:9], v1, s[6:7] offset:32
	global_load_dwordx4 v[10:13], v1, s[6:7] offset:16
	global_load_dwordx4 v[14:17], v1, s[6:7]
	global_load_dwordx4 v[18:21], v1, s[2:3] offset:48
	global_load_dwordx4 v[22:25], v1, s[2:3] offset:32
	global_load_dwordx4 v[26:29], v1, s[2:3] offset:16
	global_load_dwordx4 v[30:33], v1, s[2:3]
	global_load_dwordx4 v[34:37], v1, s[0:1] offset:48
	global_load_dwordx4 v[38:41], v1, s[0:1] offset:32
	global_load_dwordx4 v[42:45], v1, s[0:1] offset:16
	global_load_dwordx4 v[46:49], v1, s[0:1]
	global_load_dwordx4 v[52:55], v1, s[4:5] offset:48
	global_load_dwordx4 v[56:59], v1, s[4:5] offset:32
	global_load_dwordx4 v[60:63], v1, s[4:5] offset:16
	global_load_dwordx4 v[64:67], v1, s[4:5]
	s_lshl_b32 s38, s64, 3
	v_readlane_b32 s26, v251, 14
	v_readlane_b32 s65, v250, 27
	v_readlane_b32 s13, v251, 1
	v_readlane_b32 s14, v251, 2
	v_readlane_b32 s15, v251, 3
	v_readlane_b32 s27, v251, 15
	v_fmamk_f32 v0, v0, 0xbf19999a, v190
	v_readlane_b32 s12, v251, 59
	v_readlane_b32 s14, v251, 61
	v_sub_f32_e32 v203, 1.0, v0
	s_mov_b64 s[24:25], s[38:39]
	s_mov_b64 s[84:85], 0
	s_mov_b32 s23, s36
	v_readlane_b32 s13, v251, 60
	v_readlane_b32 s15, v251, 62
	s_mov_b64 s[20:21], s[44:45]
	v_readlane_b32 s16, v251, 4
	v_readlane_b32 s17, v251, 5
	s_waitcnt vmcnt(8)
	v_fma_f32 v51, v14, v30, 0
	v_fmac_f32_e32 v51, v15, v31
	s_waitcnt vmcnt(0)
	v_fma_f32 v50, v46, v64, 0
	v_fmac_f32_e32 v50, v47, v65
	v_fmac_f32_e32 v51, v16, v32
	v_fmac_f32_e32 v50, v48, v66
	v_fmac_f32_e32 v51, v17, v33
	v_fmac_f32_e32 v50, v49, v67
	v_fmac_f32_e32 v51, v10, v26
	v_fmac_f32_e32 v50, v42, v60
	v_fmac_f32_e32 v51, v11, v27
	v_fmac_f32_e32 v50, v43, v61
	v_fmac_f32_e32 v51, v12, v28
	v_fmac_f32_e32 v50, v44, v62
	v_fmac_f32_e32 v51, v13, v29
	v_fmac_f32_e32 v50, v45, v63
	v_fmac_f32_e32 v51, v6, v22
	v_fmac_f32_e32 v50, v38, v56
	v_fmac_f32_e32 v51, v7, v23
	v_fmac_f32_e32 v50, v39, v57
	v_fmac_f32_e32 v51, v8, v24
	v_fmac_f32_e32 v50, v40, v58
	v_fmac_f32_e32 v51, v9, v25
	v_fmac_f32_e32 v50, v41, v59
	v_fmac_f32_e32 v51, v2, v18
	v_fmac_f32_e32 v50, v34, v52
	v_fmac_f32_e32 v51, v3, v19
	v_fmac_f32_e32 v50, v35, v53
	v_fmac_f32_e32 v51, v4, v20
	v_fmac_f32_e32 v50, v36, v54
	v_fmac_f32_e32 v51, v5, v21
	v_fmac_f32_e32 v50, v37, v55
	global_load_dwordx4 v[2:5], v1, s[6:7] offset:112
	global_load_dwordx4 v[10:13], v1, s[6:7] offset:96
	global_load_dwordx4 v[18:21], v1, s[6:7] offset:80
	global_load_dwordx4 v[26:29], v1, s[6:7] offset:64
	global_load_dwordx4 v[6:9], v1, s[2:3] offset:112
	global_load_dwordx4 v[14:17], v1, s[2:3] offset:96
	global_load_dwordx4 v[22:25], v1, s[2:3] offset:80
	global_load_dwordx4 v[52:55], v1, s[2:3] offset:64
	global_load_dwordx4 v[30:33], v1, s[0:1] offset:112
	global_load_dwordx4 v[38:41], v1, s[0:1] offset:96
	global_load_dwordx4 v[46:49], v1, s[0:1] offset:80
	global_load_dwordx4 v[56:59], v1, s[0:1] offset:64
	global_load_dwordx4 v[34:37], v1, s[4:5] offset:112
	global_load_dwordx4 v[42:45], v1, s[4:5] offset:96
	global_load_dwordx4 v[60:63], v1, s[4:5] offset:80
	global_load_dwordx4 v[64:67], v1, s[4:5] offset:64
	s_lshl_b64 s[0:1], s[38:39], 2
	v_readlane_b32 s2, v250, 3
	s_add_u32 s2, s2, s0
	v_readlane_b32 s0, v250, 4
	s_addc_u32 s3, s0, s1
	s_lshl_b32 s0, s64, 6
	s_mov_b32 s1, s39
	s_lshl_b64 s[0:1], s[0:1], 2
	v_writelane_b32 v250, s2, 31
	s_add_u32 s0, s26, s0
	s_addc_u32 s1, s27, s1
	v_writelane_b32 v250, s3, 32
	v_writelane_b32 v250, s0, 33
	s_mov_b64 s[26:27], s[42:43]
	s_waitcnt vmcnt(8)
	v_fmac_f32_e32 v51, v26, v52
	v_fmac_f32_e32 v51, v27, v53
	v_fmac_f32_e32 v51, v28, v54
	v_fmac_f32_e32 v51, v29, v55
	v_fmac_f32_e32 v51, v18, v22
	v_fmac_f32_e32 v51, v19, v23
	v_fmac_f32_e32 v51, v20, v24
	v_fmac_f32_e32 v51, v21, v25
	s_waitcnt vmcnt(0)
	v_fmac_f32_e32 v50, v56, v64
	v_fmac_f32_e32 v51, v10, v14
	v_fmac_f32_e32 v50, v57, v65
	v_fmac_f32_e32 v51, v11, v15
	v_fmac_f32_e32 v50, v58, v66
	v_fmac_f32_e32 v51, v12, v16
	v_fmac_f32_e32 v50, v59, v67
	v_fmac_f32_e32 v51, v13, v17
	v_fmac_f32_e32 v50, v46, v60
	v_fmac_f32_e32 v51, v2, v6
	v_fmac_f32_e32 v50, v47, v61
	v_fmac_f32_e32 v51, v3, v7
	v_fmac_f32_e32 v50, v48, v62
	v_fmac_f32_e32 v51, v4, v8
	v_fmac_f32_e32 v50, v49, v63
	v_fmac_f32_e32 v51, v5, v9
	v_fmac_f32_e32 v50, v38, v42
	v_mul_f32_e32 v2, 0x3fb8aa3b, v51
	v_fmac_f32_e32 v50, v39, v43
	v_fma_f32 v3, v51, s37, -v2
	v_rndne_f32_e32 v4, v2
	v_fmac_f32_e32 v50, v40, v44
	v_fmac_f32_e32 v3, 0x32a5705f, v51
	v_sub_f32_e32 v2, v2, v4
	v_fmac_f32_e32 v50, v41, v45
	v_add_f32_e32 v2, v2, v3
	v_fmac_f32_e32 v50, v30, v34
	v_exp_f32_e32 v2, v2
	v_cvt_i32_f32_e32 v3, v4
	v_fmac_f32_e32 v50, v31, v35
	v_fmac_f32_e32 v50, v32, v36
	v_fmac_f32_e32 v50, v33, v37
	v_ldexp_f32 v2, v2, v3
	v_mul_f32_e32 v3, 0x3fb8aa3b, v50
	v_fma_f32 v4, v50, s37, -v3
	v_rndne_f32_e32 v5, v3
	v_fmac_f32_e32 v4, 0x32a5705f, v50
	v_sub_f32_e32 v3, v3, v5
	v_add_f32_e32 v3, v3, v4
	v_exp_f32_e32 v3, v3
	v_cvt_i32_f32_e32 v4, v5
	v_cmp_ngt_f32_e32 vcc, s40, v51
	v_writelane_b32 v250, s1, 34
	v_ldexp_f32 v3, v3, v4
	v_cndmask_b32_e32 v2, 0, v2, vcc
	v_cmp_nlt_f32_e32 vcc, s46, v51
	s_nop 1
	v_cndmask_b32_e32 v2, v195, v2, vcc
	v_cmp_ngt_f32_e32 vcc, s40, v50
	s_nop 1
	v_cndmask_b32_e32 v3, 0, v3, vcc
	v_cmp_nlt_f32_e32 vcc, s46, v50
	s_nop 1
	v_cndmask_b32_e32 v3, v195, v3, vcc
	v_sub_f32_e32 v2, v2, v3
	v_add_f32_e32 v202, v0, v2
	v_mov_b32_e32 v253, 1
	v_mov_b32_e32 v254, 1
	s_branch .LBB0_198

; template <int MODE>
; DI void attn_item(const Params& p, int layer, int b, int head, int qblk, u16* sm, volatile LAS int* s_done_, int wv) {
;   const int tid = tid_now(wv), lane = tid & 63, w = tid >> 6, r = lane & 31, h = lane >> 5;
;   const int q0 = qblk * 128, q0w = q0 + 32 * w, qpos = q0w + r;
;   int qoff, koff, vh, goff, yoff;
;   if (MODE == 1) { qoff = 1024 + head * 64; koff = 1536 + (head >> 2) * 64; vh = 4 + (head >> 2); goff = 1792 + head * 64; yoff = 256 + head * 64; }
;   else { qoff = 2304 + head * 64; koff = 2560 + head * 64; vh = 6 + head; goff = 3072 + head * 64; yoff = 768 + head * 64; }
;   const u16* projb = p.proj + (size_t)b * SEQ * DIN;
;   u16* Ks = sm;
;   u16* Vs = sm + 64 * LSTR;
;   bf16x8 qf[4];
; #pragma unroll
;   for (int ks = 0; ks < 4; ++ks) qf[ks] = __builtin_nontemporal_load((const bf16x8*)(projb + (size_t)qpos * DIN + qoff + 16 * ks + 8 * h));
;   float sl2 = 0.f;
;   if (MODE == 1) sl2 = exp2f(-8.f * (float)(1 + head) / 12.f) * LOG2E;
;   int lo[4];
; #pragma unroll
;   for (int c = 0; c < 4; ++c) lo[c] = r * LSTR + c * 16 + 8 * h;
;   int it0 = 0, ntiles;
;   if (MODE == 1) { ntiles = 4; it0 = (qblk == 0) ? 2 : 0; }
;   else ntiles = 2 * (qblk + 1);
;   const u16* kg = projb + koff + (tid & 7) * 8;
;   const u16* vg = p.vt + ((size_t)(b * NVH + vh) * 64) * SEQ + (tid & 7) * 8;
; __global__ void __launch_bounds__(256, 2) hymba_mega(Params p) {
;     ...
;       for (;;) {
;         __syncthreads();
;         volatile LAS int* sit = lds_fresh((volatile LAS int*)&s_item);
;         if (tid_now(wv) == 0) *sit = (int)atomicAdd(qctr, 1u);
;         __syncthreads();
;         const int item = *sit;
;         if (item >= N_ITEMS_XCD) break;
;         const int slot = (item < 128) ? 0 : (item < 192) ? 1 : 3, per = (item < 128) ? 0 : (item < 192) ? item - 128 : item - 192;
;         if (slot == 0 || slot == 2) {
;           const int ia = item;
;           if (!(rep && (0 < REP_LO || 128 > REP_HI)))
;           attn_item_A(p, layer, xcd >> 2, xcd & 3, 127 - ia, sm, lam, lam_init, wv);
;         } else if (slot == 1) {
;           if (!(rep && (128 < REP_LO || 192 > REP_HI)))
;           attn_item_B2(p, layer, (2 * xcd) >> 3, (2 * xcd) & 7, 63 - per, sm, wv);
;         } else {
;           if (!(rep && (192 < REP_LO || 256 > REP_HI)))
;           attn_item<2>(p, layer, xcd >> 2, xcd & 3, 63 - per, sm, (volatile LAS int*)s_done, wv);
.LBB0_198:
	v_mov_b32_e32 v0, 0x12020
	s_barrier
	v_mbcnt_lo_u32_b32 v2, -1, 0
	v_mbcnt_hi_u32_b32 v2, -1, v2
	s_nop 0
	v_cmp_eq_u32_e32 vcc, s41, v2
	s_and_saveexec_b64 s[0:1], vcc
	s_cbranch_execz .LBB0_202
	v_readlane_b32 s4, v250, 31
	v_readlane_b32 s5, v250, 32
	v_readlane_b32 s2, v250, 23
	v_cmp_ne_u32_e32 vcc, 0, v253
	s_cbranch_vccz .Ldq_atomic
	v_mov_b32_e32 v253, 0
	v_mov_b32_e32 v252, s2
	s_branch .Ldq_have
.Ldq_atomic:
	s_nop 4
	global_atomic_add v252, v1, v254, s[4:5] sc0
	s_waitcnt vmcnt(0)
	v_add_u32_e32 v252, 64, v252
.Ldq_have:
	ds_write_b32 v0, v252
.LBB0_201:
.LBB0_202:
	s_or_b64 exec, exec, s[0:1]
	s_waitcnt lgkmcnt(0)
	s_barrier
	ds_read_b32 v118, v0
	s_movk_i32 s0, 0x100
	s_waitcnt lgkmcnt(0)
	v_cmp_gt_i32_e32 vcc, s0, v118
	s_mov_b64 s[0:1], -1
	s_and_saveexec_b64 s[16:17], vcc
	s_cbranch_execz .LBB0_197
	s_movk_i32 s0, 0xc0
	v_cmp_gt_i32_e64 s[36:37], s0, v118
	v_cmp_gt_i32_e32 vcc, s95, v118
	s_nop 0
	v_cndmask_b32_e64 v0, 3, 1, s[36:37]
	v_cndmask_b32_e64 v0, v0, 0, vcc
	v_cmp_lt_i32_e64 s[2:3], 0, v0
	s_and_saveexec_b64 s[0:1], s[2:3]
	s_xor_b64 s[64:65], exec, s[0:1]
	s_cbranch_execz .LBB0_253
	v_cndmask_b32_e64 v2, v196, v197, s[36:37]
	v_sub_u32_e32 v2, v2, v118
	v_add_u32_e32 v2, 63, v2
	v_cndmask_b32_e64 v2, v2, 63, vcc
	v_cmp_ne_u32_e32 vcc, 1, v0
	v_lshlrev_b32_e32 v184, 7, v2
	s_and_saveexec_b64 s[0:1], vcc
	s_xor_b64 s[98:99], exec, s[0:1]
	s_cbranch_execz .LBB0_247
	v_mbcnt_lo_u32_b32 v6, -1, 0
	v_mbcnt_hi_u32_b32 v6, -1, v6
	v_readlane_b32 s0, v250, 19
	v_add_u32_e32 v5, s33, v6
	v_ashrrev_i32_e32 v168, 6, v5
	v_lshlrev_b32_e32 v3, 5, v168
	v_and_b32_e32 v169, 31, v6
	v_add_u32_e32 v148, v3, v184
	v_readlane_b32 s1, v250, 20
	v_bfe_u32 v4, v6, 5, 1
	v_or_b32_e32 v149, v148, v169
	v_mov_b64_e32 v[8:9], s[0:1]
	v_mad_i64_i32 v[8:9], s[0:1], v149, s8, v[8:9]
	v_lshlrev_b32_e32 v152, 4, v4
	v_mov_b32_e32 v153, v1
	v_lshl_add_u64 v[8:9], v[8:9], 0, v[152:153]
	s_mov_b64 s[0:1], 0x1200
	v_lshl_add_u64 v[10:11], v[8:9], 0, s[0:1]
	v_add_co_u32_e32 v8, vcc, 0x1000, v8
	v_and_b32_e32 v7, 63, v6
	s_nop 0
	v_addc_co_u32_e32 v9, vcc, 0, v9, vcc
	global_load_dwordx4 v[80:83], v[10:11], off offset:32 nt
	global_load_dwordx4 v[84:87], v[10:11], off offset:64 nt
	global_load_dwordx4 v[88:91], v[8:9], off offset:512 nt
	global_load_dwordx4 v[92:95], v[10:11], off offset:96 nt
	v_mov_b32_e32 v171, 0x12000
	v_cmp_eq_u32_e64 s[36:37], 0, v7
	v_lshl_add_u32 v172, v168, 2, v171
	s_and_saveexec_b64 s[0:1], s[36:37]
	ds_write_b32 v172, v1
	s_or_b64 exec, exec, s[0:1]
	v_readlane_b32 s0, v250, 19
	v_readlane_b32 s1, v250, 20
	v_lshlrev_b32_e32 v0, 2, v7
	v_lshrrev_b32_e32 v153, 4, v7
	v_mov_b64_e32 v[8:9], s[0:1]
	v_and_b32_e32 v170, 60, v0
	v_mad_i64_i32 v[8:9], s[0:1], v148, s8, v[8:9]
	v_lshlrev_b32_e32 v146, 1, v170
	v_mov_b32_e32 v147, v1
	v_mul_u32_u24_e32 v0, 0xd00, v153
	v_lshl_add_u64 v[8:9], v[8:9], 0, v[146:147]
	v_lshlrev_b32_e32 v0, 1, v0
	v_lshl_add_u64 v[8:9], v[8:9], 0, v[0:1]
	v_add_co_u32_e32 v10, vcc, 0x1000, v8
	s_nop 1
	v_addc_co_u32_e32 v11, vcc, 0, v9, vcc
	v_add_co_u32_e32 v12, vcc, 0x8000, v8
	s_nop 1
	v_addc_co_u32_e32 v13, vcc, 0, v9, vcc
	v_add_co_u32_e32 v14, vcc, 0xe000, v8
	s_nop 1
	v_addc_co_u32_e32 v15, vcc, 0, v9, vcc
	v_add_co_u32_e32 v16, vcc, 0x15000, v8
	s_nop 1
	v_addc_co_u32_e32 v17, vcc, 0, v9, vcc
	global_load_dwordx2 v[150:151], v[10:11], off offset:2048 nt
	global_load_dwordx2 v[144:145], v[12:13], off nt
	global_load_dwordx2 v[142:143], v[14:15], off offset:2048 nt
	global_load_dwordx2 v[140:141], v[16:17], off nt
	v_add_co_u32_e32 v10, vcc, 0x1b000, v8
	s_nop 1
	v_addc_co_u32_e32 v11, vcc, 0, v9, vcc
	v_add_co_u32_e32 v12, vcc, 0x22000, v8
	s_nop 1
	v_addc_co_u32_e32 v13, vcc, 0, v9, vcc
	v_add_co_u32_e32 v14, vcc, 0x28000, v8
	s_nop 1
	v_addc_co_u32_e32 v15, vcc, 0, v9, vcc
	v_add_co_u32_e32 v8, vcc, 0x2f000, v8
	s_nop 1
	v_addc_co_u32_e32 v9, vcc, 0, v9, vcc
	global_load_dwordx2 v[138:139], v[10:11], off offset:2048 nt
	global_load_dwordx2 v[136:137], v[12:13], off nt
	global_load_dwordx2 v[134:135], v[14:15], off offset:2048 nt
	global_load_dwordx2 v[132:133], v[8:9], off nt
	v_cmp_lt_i32_e32 vcc, -1, v2
	s_and_saveexec_b64 s[0:1], vcc
	s_xor_b64 s[0:1], exec, s[0:1]
	s_cbranch_execz .LBB0_244
	v_lshlrev_b32_e32 v0, 3, v6
	v_ashrrev_i32_e32 v154, 3, v5
	s_movk_i32 s2, 0x48
	v_lshlrev_b32_e32 v147, 1, v2
	v_and_b32_e32 v2, 56, v0
	v_mul_lo_u32 v5, v154, s2
	v_readlane_b32 s2, v250, 17
	v_lshlrev_b32_e32 v0, 1, v2
	v_readlane_b32 s3, v250, 18
	v_ashrrev_i32_e32 v155, 31, v154
	v_lshlrev_b32_e32 v8, 3, v4
	v_lshl_add_u64 v[156:157], s[2:3], 0, v[0:1]
	v_readlane_b32 s2, v250, 21
	v_readlane_b32 s3, v250, 22
	v_add_lshl_u32 v174, v5, v2, 1
	v_lshlrev_b32_e32 v2, 2, v169
	v_lshl_add_u64 v[158:159], s[2:3], 0, v[0:1]
	v_lshlrev_b32_e32 v0, 7, v4
	v_lshlrev_b64 v[160:161], 14, v[154:155]
	s_mov_b64 s[2:3], 0x80000
	v_bitop3_b32 v180, v0, s95, v2 bitop3:0x36
	v_lshl_add_u64 v[162:163], v[160:161], 0, s[2:3]
	v_lshlrev_b32_e32 v0, 1, v8
	s_movk_i32 s2, 0x90
	v_lshlrev_b32_e32 v177, 2, v4
	v_mad_u32_u24 v155, v169, s2, v0
	v_add_u32_e32 v0, v3, v169
	v_sub_u32_e32 v0, v0, v177
	v_mov_b32_e32 v14, v1
	v_mov_b32_e32 v15, v1
	v_lshlrev_b32_e32 v152, 4, v4
	v_cmp_gt_u32_e32 vcc, 32, v7
	v_subrev_u32_e32 v183, 64, v0
	v_mov_b32_e32 v0, v1
	v_mov_b32_e32 v2, v1
	v_mov_b32_e32 v3, v1
	v_mov_b32_e32 v4, v1
	v_mov_b32_e32 v5, v1
	v_mov_b32_e32 v6, v1
	v_mov_b32_e32 v7, v1
	v_mov_b32_e32 v8, v1
	v_mov_b32_e32 v9, v1
	v_mov_b32_e32 v10, v1
	v_mov_b32_e32 v11, v1
	v_mov_b32_e32 v12, v1
	v_mov_b32_e32 v13, v1
	v_mov_b64_e32 v[30:31], v[14:15]
	v_mov_b64_e32 v[46:47], v[14:15]
	v_add_u32_e32 v173, 2, v147
	v_add_u32_e32 v175, 0x2400, v174
	v_or_b32_e32 v176, 31, v148
	v_mul_u32_u24_e32 v181, 0x90, v169
	v_add_u32_e32 v182, 0x2400, v155
	v_add_u32_e32 v164, 64, v184
	s_mov_b32 s87, 0
	v_mov_b32_e32 v184, 0
	v_mov_b32_e32 v64, 0
	s_mov_b64 s[46:47], 0
	v_mov_b64_e32 v[28:29], v[12:13]
	v_mov_b64_e32 v[26:27], v[10:11]
	v_mov_b64_e32 v[24:25], v[8:9]
	v_mov_b64_e32 v[22:23], v[6:7]
	v_mov_b64_e32 v[20:21], v[4:5]
	v_mov_b64_e32 v[18:19], v[2:3]
	v_mov_b64_e32 v[16:17], v[0:1]
	v_mov_b64_e32 v[44:45], v[12:13]
	v_mov_b64_e32 v[42:43], v[10:11]
	v_mov_b64_e32 v[40:41], v[8:9]
	v_mov_b64_e32 v[38:39], v[6:7]
	v_mov_b64_e32 v[36:37], v[4:5]
	v_mov_b64_e32 v[34:35], v[2:3]
	v_mov_b64_e32 v[32:33], v[0:1]
	s_branch .LBB0_211
